# DSA tile body in two orders: waves 4-7 run S0,softmax0,S1,softmax1,PV0,PV1 so their matrix and vector segments alternate with waves 0-3
# speedup vs baseline: 1.0058x; 1.0058x over previous
; #define GAS __attribute__((address_space(1)))
; __device__ __forceinline__ void dsa_unit32(const Args& a, LAS unsigned char* lds, const LAS unsigned long long* maskl, int b, int qb, int tid, int wave, int lane) {
;     ...
;     const int l31 = lane & 31, hi = lane >> 5, t0 = qb * 32, h = wave; const size_t rowb = (size_t)b * SEQ;
;     bf16x8 qf[8]; float qs = 0.f;
; #pragma unroll
;     for (int ks = 0; ks < 8; ++ks) { const u32x4 w = __builtin_nontemporal_load((const GAS u32x4*)(z + (rowb + t0 + l31) * ZW + ZDQ + h * 128 + 16 * ks + 8 * hi)); qf[ks] = __builtin_bit_cast(bf16x8, w);
; #pragma unroll
;         for (int i = 0; i < 4; ++i) { const float x0 = bflo(w[i]), x1 = bfhi(w[i]); qs += x0 * x0 + x1 * x1; } }
;     qs += __shfl_xor(qs, 32);
;     const float negB = -1.01f * 11.313708498984761f * sqrtf(qs);
;     const int nkt = (t0 + 32 + 63) >> 6;
;     f32x16 O[4];
; #pragma unroll
;     for (int ct = 0; ct < 4; ++ct)
; #pragma unroll
;         for (int i = 0; i < 16; ++i) O[ct][i] = 0.f;
;     float l = 0.f;
;     u32x4 rk0[2], rv0[2], rk1[2], rv1[2];
;     const unsigned vok0 = (unsigned)((tid >> 4) * 128 + 8 * (tid & 15)) * 2u, vok1 = vok0 + 32u * 128u * 2u;
;     const unsigned vov0 = (unsigned)((tid >> 3) * SEQ + 8 * (tid & 7)) * 2u, vov1 = vov0 + 64u * (unsigned)SEQ * 2u;
;     const GAS char* ckb = (const GAS char*)ckv + (size_t)rowb * 256; const GAS char* cvb = (const GAS char*)ckvT + (size_t)b * 128 * SEQ * 2;
.LBB0_1298:
	v_readlane_b32 s17, v254, 4
	v_readlane_b32 s0, v254, 43
	v_mov_b32_e32 v15, v252
	s_lshl_b32 s4, s0, 5
	v_readlane_b32 s0, v254, 46
	s_add_i32 s0, s0, s4
	v_and_b32_e32 v5, 31, v15
	v_or_b32_e32 v178, s0, v5
	v_readlane_b32 s0, v254, 24
	v_readlane_b32 s1, v254, 25
	v_bfe_u32 v14, v15, 5, 1
	v_lshlrev_b32_e32 v180, 4, v14
	s_movk_i32 s0, 0x1e00
	v_readlane_b32 s0, v254, 38
	v_readlane_b32 s1, v254, 39
	s_mov_b32 s1, s19
	v_mov_b32_e32 v181, v4
	s_mov_b32 s2, s0
	s_mov_b64 s[0:1], 0x1000
	v_writelane_b32 v254, s2, 38
	s_movk_i32 s0, 0xf000
	s_waitcnt vmcnt(0)
	v_and_b32_e32 v7, 0xffff0000, v0
	v_and_b32_e32 v33, 0xffff0000, v126
	v_and_b32_e32 v35, 0xffff0000, v127
	v_lshlrev_b32_e32 v32, 16, v126
	v_lshlrev_b32_e32 v34, 16, v127
	v_and_b32_e32 v37, 0xffff0000, v128
	v_mul_f32_e32 v33, v33, v33
	v_mul_f32_e32 v35, v35, v35
	v_lshlrev_b32_e32 v6, 16, v0
	v_lshlrev_b32_e32 v36, 16, v128
	v_and_b32_e32 v39, 0xffff0000, v129
	v_mul_f32_e32 v7, v7, v7
	v_mul_f32_e32 v37, v37, v37
	v_fmac_f32_e32 v33, v32, v32
	v_fmac_f32_e32 v35, v34, v34
	v_lshlrev_b32_e32 v38, 16, v129
	v_mul_f32_e32 v39, v39, v39
	v_fmac_f32_e32 v7, v6, v6
	v_fmac_f32_e32 v37, v36, v36
	v_add_f32_e32 v6, v33, v35
	v_and_b32_e32 v9, 0xffff0000, v1
	v_fmac_f32_e32 v39, v38, v38
	v_add_f32_e32 v6, v37, v6
	v_lshlrev_b32_e32 v8, 16, v1
	v_and_b32_e32 v11, 0xffff0000, v2
	v_mul_f32_e32 v9, v9, v9
	v_add_f32_e32 v6, v39, v6
	v_lshlrev_b32_e32 v10, 16, v2
	v_and_b32_e32 v13, 0xffff0000, v3
	v_mul_f32_e32 v11, v11, v11
	v_fmac_f32_e32 v9, v8, v8
	v_add_f32_e32 v6, v7, v6
	v_lshlrev_b32_e32 v12, 16, v3
	v_and_b32_e32 v17, 0xffff0000, v118
	v_mul_f32_e32 v13, v13, v13
	v_fmac_f32_e32 v11, v10, v10
	v_add_f32_e32 v6, v9, v6
	v_lshlrev_b32_e32 v16, 16, v118
	v_and_b32_e32 v19, 0xffff0000, v119
	v_mul_f32_e32 v17, v17, v17
	v_fmac_f32_e32 v13, v12, v12
	v_add_f32_e32 v6, v11, v6
	v_lshlrev_b32_e32 v18, 16, v119
	v_and_b32_e32 v21, 0xffff0000, v120
	v_mul_f32_e32 v19, v19, v19
	v_fmac_f32_e32 v17, v16, v16
	v_add_f32_e32 v6, v13, v6
	v_lshlrev_b32_e32 v20, 16, v120
	v_and_b32_e32 v23, 0xffff0000, v121
	v_mul_f32_e32 v21, v21, v21
	v_fmac_f32_e32 v19, v18, v18
	v_add_f32_e32 v6, v17, v6
	v_lshlrev_b32_e32 v22, 16, v121
	v_and_b32_e32 v25, 0xffff0000, v122
	v_mul_f32_e32 v23, v23, v23
	v_fmac_f32_e32 v21, v20, v20
	v_add_f32_e32 v6, v19, v6
	v_lshlrev_b32_e32 v24, 16, v122
	v_and_b32_e32 v27, 0xffff0000, v123
	v_mul_f32_e32 v25, v25, v25
	v_fmac_f32_e32 v23, v22, v22
	v_add_f32_e32 v6, v21, v6
	v_lshlrev_b32_e32 v26, 16, v123
	v_and_b32_e32 v29, 0xffff0000, v124
	v_mul_f32_e32 v27, v27, v27
	v_fmac_f32_e32 v25, v24, v24
	v_add_f32_e32 v6, v23, v6
	v_lshlrev_b32_e32 v28, 16, v124
	v_and_b32_e32 v31, 0xffff0000, v125
	v_mul_f32_e32 v29, v29, v29
	v_fmac_f32_e32 v27, v26, v26
	v_add_f32_e32 v6, v25, v6
	v_lshlrev_b32_e32 v30, 16, v125
	v_mul_f32_e32 v31, v31, v31
	v_fmac_f32_e32 v29, v28, v28
	v_add_f32_e32 v6, v27, v6
	v_and_b32_e32 v8, 0xffff0000, v130
	v_add_f32_e32 v6, v29, v6
	v_fmac_f32_e32 v31, v30, v30
	v_lshlrev_b32_e32 v7, 16, v130
	v_mul_f32_e32 v8, v8, v8
	v_add_f32_e32 v6, v31, v6
	v_fmac_f32_e32 v8, v7, v7
	v_add_f32_e32 v6, v8, v6
	v_and_b32_e32 v8, 0xffff0000, v131
	v_lshlrev_b32_e32 v7, 16, v131
	v_mul_f32_e32 v8, v8, v8
	v_fmac_f32_e32 v8, v7, v7
	v_add_f32_e32 v7, v8, v6
	v_lshlrev_b32_e32 v6, 4, v15
	v_writelane_b32 v254, s3, 39
	v_lshlrev_b32_e32 v10, 9, v15
	v_and_b32_e32 v16, 0x70, v6
	v_and_or_b32 v10, v10, s0, v16
	v_readlane_b32 s0, v254, 45
	s_lshl_b32 s18, s0, 19
	v_readlane_b32 s8, v254, 41
	v_readlane_b32 s9, v254, 42
	s_add_u32 s0, s8, s18
	s_addc_u32 s1, s9, 0
	v_readlane_b32 s2, v254, 28
	v_readlane_b32 s3, v254, 29
	s_add_u32 s2, s2, s18
	v_add_u32_e32 v8, 0x2000, v6
	v_add_u32_e32 v12, 0x40000, v10
	s_addc_u32 s3, s3, 0
	v_and_b32_e32 v11, 0xffff0000, v132
	v_lshlrev_b32_e32 v9, 16, v132
	v_mul_f32_e32 v11, v11, v11
	v_fmac_f32_e32 v11, v9, v9
	v_add_f32_e32 v7, v11, v7
	v_and_b32_e32 v11, 0xffff0000, v133
	v_lshlrev_b32_e32 v9, 16, v133
	v_mul_f32_e32 v11, v11, v11
	v_fmac_f32_e32 v11, v9, v9
	v_add_f32_e32 v7, v11, v7
	v_and_b32_e32 v11, 0xffff0000, v134
	v_lshlrev_b32_e32 v9, 16, v134
	v_mul_f32_e32 v11, v11, v11
	v_fmac_f32_e32 v11, v9, v9
	v_add_f32_e32 v7, v11, v7
	v_and_b32_e32 v11, 0xffff0000, v135
	v_lshlrev_b32_e32 v9, 16, v135
	v_mul_f32_e32 v11, v11, v11
	v_fmac_f32_e32 v11, v9, v9
	v_add_f32_e32 v7, v11, v7
	v_and_b32_e32 v11, 0xffff0000, v136
	v_lshlrev_b32_e32 v9, 16, v136
	v_mul_f32_e32 v11, v11, v11
	v_fmac_f32_e32 v11, v9, v9
	v_add_f32_e32 v7, v11, v7
	v_and_b32_e32 v11, 0xffff0000, v137
	v_lshlrev_b32_e32 v9, 16, v137
	v_mul_f32_e32 v11, v11, v11
	v_fmac_f32_e32 v11, v9, v9
	v_add_f32_e32 v7, v11, v7
	v_and_b32_e32 v11, 0xffff0000, v138
	v_lshlrev_b32_e32 v9, 16, v138
	v_mul_f32_e32 v11, v11, v11
	v_fmac_f32_e32 v11, v9, v9
	v_add_f32_e32 v7, v11, v7
	v_and_b32_e32 v11, 0xffff0000, v139
	v_lshlrev_b32_e32 v9, 16, v139
	v_mul_f32_e32 v11, v11, v11
	v_fmac_f32_e32 v11, v9, v9
	v_add_f32_e32 v7, v11, v7
	v_and_b32_e32 v11, 0xffff0000, v140
	v_lshlrev_b32_e32 v9, 16, v140
	v_mul_f32_e32 v11, v11, v11
	v_fmac_f32_e32 v11, v9, v9
	v_add_f32_e32 v7, v11, v7
	v_and_b32_e32 v11, 0xffff0000, v141
	v_lshlrev_b32_e32 v9, 16, v141
	v_mul_f32_e32 v11, v11, v11
	v_fmac_f32_e32 v11, v9, v9
	v_add_f32_e32 v7, v11, v7
	v_and_b32_e32 v11, 0xffff0000, v142
	v_lshlrev_b32_e32 v9, 16, v142
	v_mul_f32_e32 v11, v11, v11
	v_fmac_f32_e32 v11, v9, v9
	v_add_f32_e32 v7, v11, v7
	v_and_b32_e32 v11, 0xffff0000, v143
	v_lshlrev_b32_e32 v9, 16, v143
	v_mul_f32_e32 v11, v11, v11
	v_fmac_f32_e32 v11, v9, v9
	v_add_f32_e32 v7, v11, v7
	v_and_b32_e32 v11, 0xffff0000, v144
	v_lshlrev_b32_e32 v9, 16, v144
	v_mul_f32_e32 v11, v11, v11
	v_fmac_f32_e32 v11, v9, v9
	v_add_f32_e32 v7, v11, v7
	v_and_b32_e32 v11, 0xffff0000, v145
	v_lshlrev_b32_e32 v9, 16, v145
	v_mul_f32_e32 v11, v11, v11
	v_fmac_f32_e32 v11, v9, v9
	v_add_f32_e32 v17, v11, v7
	v_xor_b32_e32 v7, 32, v253
	v_cmp_lt_i32_e32 vcc, v7, v226
	v_mov_b32_e32 v9, v4
	v_mov_b32_e32 v11, v4
	v_cndmask_b32_e32 v7, v253, v7, vcc
	v_lshlrev_b32_e32 v181, 2, v7
	ds_bpermute_b32 v18, v181, v17
	v_mov_b32_e32 v7, v4
	s_cmp_lt_u32 s4, 33
	v_mov_b32_e32 v13, v4
	s_cbranch_scc1 .LBB0_1300
	s_add_u32 s0, s0, 0x4000
	s_addc_u32 s1, s1, 0
	v_lshl_add_u64 v[26:27], s[0:1], 0, v[6:7]
	v_lshl_add_u64 v[20:21], s[2:3], 0, v[10:11]
	v_lshl_add_u64 v[22:23], s[2:3], 0, v[12:13]
	v_lshl_add_u64 v[24:25], s[0:1], 0, v[8:9]

; #define LAS __attribute__((address_space(3)))
; __device__ __forceinline__ f32x16 mfma32(bf16x8 a, bf16x8 b, f32x16 c) { return __builtin_amdgcn_mfma_f32_32x32x16_bf16(a, b, c, 0, 0, 0); }
; __device__ __forceinline__ void dsa_unit32(const Args& a, LAS unsigned char* lds, const LAS unsigned long long* maskl, int b, int qb, int tid, int wave, int lane) {
;     ...
;         const unsigned long long mw = maskl[l31 * 32 + kt];
;         const LAS bf16* Ks = (const LAS bf16*)(lds + buf * STG); const LAS bf16* Vs = (const LAS bf16*)(lds + buf * STG + KBYTES);
;         f32x16 S2[2];
; #pragma unroll
;         for (int kh = 0; kh < 2; ++kh) {
; #pragma unroll
;             for (int i = 0; i < 16; ++i) S2[kh][i] = negB;
;             __builtin_amdgcn_s_setprio(1);
; #pragma unroll
;             for (int ks = 0; ks < 8; ++ks) S2[kh] = mfma32(*(const LAS bf16x8*)(Ks + (32 * kh + l31) * KS + 16 * ks + 8 * hi), qf[ks], S2[kh]);
;             __builtin_amdgcn_s_setprio(0);
;         }
; #pragma unroll
;         for (int kh = 0; kh < 2; ++kh) {
;             const unsigned mh = (unsigned)(mw >> (32 * kh + 4 * hi));
;             float p[16];
; #pragma unroll
;             for (int i = 0; i < 16; ++i) { const float e = __builtin_amdgcn_exp2f(S2[kh][i]);
;                 const int keep = __builtin_amdgcn_sbfe((int)mh, 8 * (i >> 2) + (i & 3), 1);
;                 p[i] = __builtin_bit_cast(float, __builtin_bit_cast(int, e) & keep); l += p[i]; }
.LBB0_1304:
	s_cmp_lt_u32 s17, 4
	s_cbranch_scc0 .Ldsa_B0
	v_add_u32_e32 v207, -8, v206
	ds_read_b64 v[220:221], v207
	v_add_u32_e32 v207, v202, v180
	ds_read_b128 v[216:219], v207 offset:0
	ds_read_b128 v[228:231], v207 offset:32
	ds_read_b128 v[232:235], v207 offset:64
	ds_read_b128 v[236:239], v207 offset:96
	ds_read_b128 v[240:243], v207 offset:128
	ds_read_b128 v[244:247], v207 offset:160
	ds_read_b128 v[248:251], v207 offset:192
	ds_read_b128 v[222:225], v207 offset:224
	ds_read_b128 v[208:211], v207 offset:8704
	ds_read_b128 v[212:215], v207 offset:8736
	s_setprio 1
	s_waitcnt lgkmcnt(9)
	v_mfma_f32_32x32x16_bf16 v[102:117], v[216:219], v[126:129], v[70:85]
	ds_read_b128 v[216:219], v207 offset:8768
	s_waitcnt lgkmcnt(9)
	v_mfma_f32_32x32x16_bf16 v[102:117], v[228:231], v[0:3], v[102:117]
	ds_read_b128 v[228:231], v207 offset:8800
	s_waitcnt lgkmcnt(9)
	v_mfma_f32_32x32x16_bf16 v[102:117], v[232:235], v[118:121], v[102:117]
	ds_read_b128 v[232:235], v207 offset:8832
	s_waitcnt lgkmcnt(9)
	v_mfma_f32_32x32x16_bf16 v[102:117], v[236:239], v[122:125], v[102:117]
	ds_read_b128 v[236:239], v207 offset:8864
	s_waitcnt lgkmcnt(9)
	v_mfma_f32_32x32x16_bf16 v[102:117], v[240:243], v[130:133], v[102:117]
	ds_read_b128 v[240:243], v207 offset:8896
	s_waitcnt lgkmcnt(9)
	v_mfma_f32_32x32x16_bf16 v[102:117], v[244:247], v[134:137], v[102:117]
	ds_read_b128 v[244:247], v207 offset:8928
	s_waitcnt lgkmcnt(9)
	v_mfma_f32_32x32x16_bf16 v[102:117], v[248:251], v[138:141], v[102:117]
	s_waitcnt lgkmcnt(8)
	v_mfma_f32_32x32x16_bf16 v[102:117], v[222:225], v[142:145], v[102:117]
	s_waitcnt lgkmcnt(7)
	v_mfma_f32_32x32x16_bf16 v[86:101], v[208:211], v[126:129], v[70:85]
	s_waitcnt lgkmcnt(6)
	v_mfma_f32_32x32x16_bf16 v[86:101], v[212:215], v[0:3], v[86:101]
	s_waitcnt lgkmcnt(5)
	v_mfma_f32_32x32x16_bf16 v[86:101], v[216:219], v[118:121], v[86:101]
	v_add_u32_e32 v207, 17408, v203
	ds_read2_b64 v[248:251], v207 offset0:0 offset1:2
	ds_read2_b64 v[222:225], v207 offset0:4 offset1:6
	v_add_u32_e32 v207, 22272, v203
	ds_read2_b64 v[216:219], v207 offset0:0 offset1:2
	s_waitcnt lgkmcnt(7)
	v_mfma_f32_32x32x16_bf16 v[86:101], v[228:231], v[122:125], v[86:101]
	ds_read2_b64 v[228:231], v207 offset0:4 offset1:6
	s_waitcnt lgkmcnt(7)
	v_mfma_f32_32x32x16_bf16 v[86:101], v[232:235], v[130:133], v[86:101]
	v_add_u32_e32 v207, 27136, v203
	ds_read2_b64 v[232:235], v207 offset0:0 offset1:2
	s_waitcnt lgkmcnt(7)
	v_mfma_f32_32x32x16_bf16 v[86:101], v[236:239], v[134:137], v[86:101]
	ds_read2_b64 v[236:239], v207 offset0:4 offset1:6
	s_waitcnt lgkmcnt(7)
	v_mfma_f32_32x32x16_bf16 v[86:101], v[240:243], v[138:141], v[86:101]
	v_add_u32_e32 v207, 32000, v203
	ds_read2_b64 v[240:243], v207 offset0:0 offset1:2
	s_waitcnt lgkmcnt(7)
	v_mfma_f32_32x32x16_bf16 v[86:101], v[244:247], v[142:145], v[86:101]
	ds_read2_b64 v[244:247], v207 offset0:4 offset1:6
	s_setprio 0
	v_lshrrev_b64 v[208:209], v182, v[220:221]
	v_exp_f32_e32 v102, v102
	v_bfe_i32 v209, v208, 0, 1
	v_exp_f32_e32 v103, v103
	v_bfe_i32 v210, v208, 1, 1
	v_and_b32_e32 v102, v102, v209
	v_exp_f32_e32 v104, v104
	v_bfe_i32 v211, v208, 2, 1
	v_and_b32_e32 v103, v103, v210
	v_exp_f32_e32 v105, v105
	v_bfe_i32 v209, v208, 3, 1
	v_and_b32_e32 v104, v104, v211
	v_exp_f32_e32 v106, v106
	v_bfe_i32 v210, v208, 8, 1
	v_and_b32_e32 v105, v105, v209
	v_exp_f32_e32 v107, v107
	v_bfe_i32 v211, v208, 9, 1
	v_and_b32_e32 v106, v106, v210
	v_exp_f32_e32 v108, v108
	v_bfe_i32 v209, v208, 10, 1
	v_and_b32_e32 v107, v107, v211
	v_exp_f32_e32 v109, v109
	v_bfe_i32 v210, v208, 11, 1
	v_and_b32_e32 v108, v108, v209
	v_exp_f32_e32 v110, v110
	v_bfe_i32 v211, v208, 16, 1
	v_and_b32_e32 v109, v109, v210
	v_exp_f32_e32 v111, v111
	v_bfe_i32 v209, v208, 17, 1
	v_and_b32_e32 v110, v110, v211
	v_exp_f32_e32 v112, v112
	v_bfe_i32 v210, v208, 18, 1
	v_and_b32_e32 v111, v111, v209
	v_exp_f32_e32 v113, v113
	v_bfe_i32 v211, v208, 19, 1
	v_and_b32_e32 v112, v112, v210
	v_exp_f32_e32 v114, v114
	v_bfe_i32 v209, v208, 24, 1
	v_and_b32_e32 v113, v113, v211
	v_exp_f32_e32 v115, v115
	v_bfe_i32 v210, v208, 25, 1
	v_and_b32_e32 v114, v114, v209
	v_exp_f32_e32 v116, v116
	v_bfe_i32 v211, v208, 26, 1
	v_and_b32_e32 v115, v115, v210
	v_exp_f32_e32 v117, v117
	v_bfe_i32 v209, v208, 27, 1
	v_and_b32_e32 v116, v116, v211
	s_nop 0
	v_and_b32_e32 v117, v117, v209
	v_cvt_pk_bf16_f32 v208, v102, v103
	v_cvt_pk_bf16_f32 v209, v104, v105
	v_cvt_pk_bf16_f32 v210, v106, v107
	v_cvt_pk_bf16_f32 v211, v108, v109
	v_cvt_pk_bf16_f32 v212, v110, v111
	v_cvt_pk_bf16_f32 v213, v112, v113
	v_cvt_pk_bf16_f32 v214, v114, v115
	v_cvt_pk_bf16_f32 v215, v116, v117
	s_nop 1
	s_setprio 1
	s_waitcnt lgkmcnt(7)
	v_mfma_f32_32x32x16_bf16 v[54:69], v[248:251], v[208:211], v[54:69]
	v_add_u32_e32 v207, 17408, v203
	ds_read2_b64 v[248:251], v207 offset0:8 offset1:10
	v_add_f32_e32 v194, v194, v102
	v_add_f32_e32 v194, v103, v194
	s_waitcnt lgkmcnt(7)
	v_mfma_f32_32x32x16_bf16 v[54:69], v[222:225], v[212:215], v[54:69]
	ds_read2_b64 v[222:225], v207 offset0:12 offset1:14
	v_add_f32_e32 v194, v104, v194
	v_add_f32_e32 v194, v105, v194
	s_waitcnt lgkmcnt(7)
	v_mfma_f32_32x32x16_bf16 v[38:53], v[216:219], v[208:211], v[38:53]
	v_add_u32_e32 v207, 22272, v203
	ds_read2_b64 v[216:219], v207 offset0:8 offset1:10
	v_add_f32_e32 v194, v106, v194
	v_add_f32_e32 v194, v107, v194
	s_waitcnt lgkmcnt(7)
	v_mfma_f32_32x32x16_bf16 v[38:53], v[228:231], v[212:215], v[38:53]
	ds_read2_b64 v[228:231], v207 offset0:12 offset1:14
	v_add_f32_e32 v194, v108, v194
	v_add_f32_e32 v194, v109, v194
	s_waitcnt lgkmcnt(7)
; #define LAS __attribute__((address_space(3)))
; __device__ __forceinline__ unsigned pk2(float lo, float hi) { f32x2_t v = {lo, hi}; bf16x2_t b = __builtin_convertvector(v, bf16x2_t); return __builtin_bit_cast(unsigned, b); }
; __device__ __forceinline__ void dsa_unit32(const Args& a, LAS unsigned char* lds, const LAS unsigned long long* maskl, int b, int qb, int tid, int wave, int lane) {
;     ...
;         const unsigned long long mw = maskl[l31 * 32 + kt];
;         const LAS bf16* Ks = (const LAS bf16*)(lds + buf * STG); const LAS bf16* Vs = (const LAS bf16*)(lds + buf * STG + KBYTES);
;         f32x16 S2[2];
; #pragma unroll
;         for (int kh = 0; kh < 2; ++kh) {
; #pragma unroll
;             for (int i = 0; i < 16; ++i) S2[kh][i] = negB;
;             __builtin_amdgcn_s_setprio(1);
; #pragma unroll
;             for (int ks = 0; ks < 8; ++ks) S2[kh] = mfma32(*(const LAS bf16x8*)(Ks + (32 * kh + l31) * KS + 16 * ks + 8 * hi), qf[ks], S2[kh]);
;             __builtin_amdgcn_s_setprio(0);
;     ...
;         for (int kh = 0; kh < 2; ++kh) {
;             const unsigned mh = (unsigned)(mw >> (32 * kh + 4 * hi));
;             float p[16];
; #pragma unroll
;             for (int i = 0; i < 16; ++i) { const float e = __builtin_amdgcn_exp2f(S2[kh][i]);
;                 const int keep = __builtin_amdgcn_sbfe((int)mh, 8 * (i >> 2) + (i & 3), 1);
;                 p[i] = __builtin_bit_cast(float, __builtin_bit_cast(int, e) & keep); l += p[i]; }
;             u32x4 w0, w1;
;             w0.x = pk2(p[0], p[1]); w0.y = pk2(p[2], p[3]); w0.z = pk2(p[4], p[5]); w0.w = pk2(p[6], p[7]);
;             w1.x = pk2(p[8], p[9]); w1.y = pk2(p[10], p[11]); w1.z = pk2(p[12], p[13]); w1.w = pk2(p[14], p[15]);
;             const bf16x8 pa = __builtin_bit_cast(bf16x8, w0), pb = __builtin_bit_cast(bf16x8, w1);
;             __builtin_amdgcn_s_setprio(1);
; #pragma unroll
;             for (int ct = 0; ct < 4; ++ct) {
;                 const LAS bf16* vr = Vs + (32 * ct + l31) * VS + 4 * hi + 32 * kh;
;                 O[ct] = mfma32(cat8(*(const LAS u32x2*)(vr), *(const LAS u32x2*)(vr + 8)), pa, O[ct]);
;                 O[ct] = mfma32(cat8(*(const LAS u32x2*)(vr + 16), *(const LAS u32x2*)(vr + 24)), pb, O[ct]);
;             }
;             __builtin_amdgcn_s_setprio(0);
;         }
	v_mfma_f32_32x32x16_bf16 v[22:37], v[232:235], v[208:211], v[22:37]
	v_add_u32_e32 v207, 27136, v203
	ds_read2_b64 v[232:235], v207 offset0:8 offset1:10
	v_add_f32_e32 v194, v110, v194
	v_add_f32_e32 v194, v111, v194
	s_waitcnt lgkmcnt(7)
	v_mfma_f32_32x32x16_bf16 v[22:37], v[236:239], v[212:215], v[22:37]
	ds_read2_b64 v[236:239], v207 offset0:12 offset1:14
	v_add_f32_e32 v194, v112, v194
	v_add_f32_e32 v194, v113, v194
	s_waitcnt lgkmcnt(7)
	v_mfma_f32_32x32x16_bf16 v[6:21], v[240:243], v[208:211], v[6:21]
	v_add_u32_e32 v207, 32000, v203
	ds_read2_b64 v[240:243], v207 offset0:8 offset1:10
	v_add_f32_e32 v194, v114, v194
	v_add_f32_e32 v194, v115, v194
	s_waitcnt lgkmcnt(7)
	v_mfma_f32_32x32x16_bf16 v[6:21], v[244:247], v[212:215], v[6:21]
	ds_read2_b64 v[244:247], v207 offset0:12 offset1:14
	v_add_f32_e32 v194, v116, v194
	v_add_f32_e32 v194, v117, v194
	s_setprio 0
	v_lshrrev_b64 v[208:209], v184, v[220:221]
	v_exp_f32_e32 v86, v86
	v_bfe_i32 v209, v208, 0, 1
	v_exp_f32_e32 v87, v87
	v_bfe_i32 v210, v208, 1, 1
	v_and_b32_e32 v86, v86, v209
	v_exp_f32_e32 v88, v88
	v_bfe_i32 v211, v208, 2, 1
	v_and_b32_e32 v87, v87, v210
	v_exp_f32_e32 v89, v89
	v_bfe_i32 v209, v208, 3, 1
	v_and_b32_e32 v88, v88, v211
	v_exp_f32_e32 v90, v90
	v_bfe_i32 v210, v208, 8, 1
	v_and_b32_e32 v89, v89, v209
	v_exp_f32_e32 v91, v91
	v_bfe_i32 v211, v208, 9, 1
	v_and_b32_e32 v90, v90, v210
	v_exp_f32_e32 v92, v92
	v_bfe_i32 v209, v208, 10, 1
	v_and_b32_e32 v91, v91, v211
	v_exp_f32_e32 v93, v93
	v_bfe_i32 v210, v208, 11, 1
	v_and_b32_e32 v92, v92, v209
	v_exp_f32_e32 v94, v94
	v_bfe_i32 v211, v208, 16, 1
	v_and_b32_e32 v93, v93, v210
	v_exp_f32_e32 v95, v95
	v_bfe_i32 v209, v208, 17, 1
	v_and_b32_e32 v94, v94, v211
	v_exp_f32_e32 v96, v96
	v_bfe_i32 v210, v208, 18, 1
	v_and_b32_e32 v95, v95, v209
	v_exp_f32_e32 v97, v97
	v_bfe_i32 v211, v208, 19, 1
	v_and_b32_e32 v96, v96, v210
	v_exp_f32_e32 v98, v98
	v_bfe_i32 v209, v208, 24, 1
	v_and_b32_e32 v97, v97, v211
	v_exp_f32_e32 v99, v99
	v_bfe_i32 v210, v208, 25, 1
	v_and_b32_e32 v98, v98, v209
	v_exp_f32_e32 v100, v100
	v_bfe_i32 v211, v208, 26, 1
	v_and_b32_e32 v99, v99, v210
	v_exp_f32_e32 v101, v101
	v_bfe_i32 v209, v208, 27, 1
	v_and_b32_e32 v100, v100, v211
	s_nop 0
	v_and_b32_e32 v101, v101, v209
	v_cvt_pk_bf16_f32 v208, v86, v87
	v_cvt_pk_bf16_f32 v209, v88, v89
	v_cvt_pk_bf16_f32 v210, v90, v91
	v_cvt_pk_bf16_f32 v211, v92, v93
	v_cvt_pk_bf16_f32 v212, v94, v95
	v_cvt_pk_bf16_f32 v213, v96, v97
	v_cvt_pk_bf16_f32 v214, v98, v99
	v_cvt_pk_bf16_f32 v215, v100, v101
	s_nop 1
	s_setprio 1
	s_waitcnt lgkmcnt(7)
	v_mfma_f32_32x32x16_bf16 v[54:69], v[248:251], v[208:211], v[54:69]
	v_add_f32_e32 v194, v194, v86
	v_add_f32_e32 v194, v87, v194
	s_waitcnt lgkmcnt(6)
	v_mfma_f32_32x32x16_bf16 v[54:69], v[222:225], v[212:215], v[54:69]
	v_add_f32_e32 v194, v88, v194
	v_add_f32_e32 v194, v89, v194
	s_waitcnt lgkmcnt(5)
	v_mfma_f32_32x32x16_bf16 v[38:53], v[216:219], v[208:211], v[38:53]
	v_add_f32_e32 v194, v90, v194
	v_add_f32_e32 v194, v91, v194
	s_waitcnt lgkmcnt(4)
	v_mfma_f32_32x32x16_bf16 v[38:53], v[228:231], v[212:215], v[38:53]
	v_add_f32_e32 v194, v92, v194
	v_add_f32_e32 v194, v93, v194
	s_waitcnt lgkmcnt(3)
	v_mfma_f32_32x32x16_bf16 v[22:37], v[232:235], v[208:211], v[22:37]
	v_add_f32_e32 v194, v94, v194
	v_add_f32_e32 v194, v95, v194
	s_waitcnt lgkmcnt(2)
	v_mfma_f32_32x32x16_bf16 v[22:37], v[236:239], v[212:215], v[22:37]
	v_add_f32_e32 v194, v96, v194
	v_add_f32_e32 v194, v97, v194
	s_waitcnt lgkmcnt(1)
	v_mfma_f32_32x32x16_bf16 v[6:21], v[240:243], v[208:211], v[6:21]
	v_add_f32_e32 v194, v98, v194
	v_add_f32_e32 v194, v99, v194
	s_waitcnt lgkmcnt(0)
	v_mfma_f32_32x32x16_bf16 v[6:21], v[244:247], v[212:215], v[6:21]
	v_add_f32_e32 v194, v100, v194
	v_add_f32_e32 v194, v101, v194
	s_setprio 0
	s_branch .Ldsa_J0
.Ldsa_B0:
	v_add_u32_e32 v207, -8, v206
	ds_read_b64 v[220:221], v207
	v_add_u32_e32 v207, v202, v180
	ds_read_b128 v[216:219], v207 offset:0
	ds_read_b128 v[228:231], v207 offset:32
	ds_read_b128 v[232:235], v207 offset:64
	ds_read_b128 v[236:239], v207 offset:96
	ds_read_b128 v[240:243], v207 offset:128
	ds_read_b128 v[244:247], v207 offset:160
	ds_read_b128 v[248:251], v207 offset:192
	ds_read_b128 v[222:225], v207 offset:224
	s_setprio 1
	s_waitcnt lgkmcnt(7)
	v_mfma_f32_32x32x16_bf16 v[102:117], v[216:219], v[126:129], v[70:85]
	ds_read_b128 v[216:219], v207 offset:8704
	s_waitcnt lgkmcnt(7)
	v_mfma_f32_32x32x16_bf16 v[102:117], v[228:231], v[0:3], v[102:117]
	ds_read_b128 v[228:231], v207 offset:8736
	s_waitcnt lgkmcnt(7)
	v_mfma_f32_32x32x16_bf16 v[102:117], v[232:235], v[118:121], v[102:117]
	ds_read_b128 v[232:235], v207 offset:8768
	s_waitcnt lgkmcnt(7)
	v_mfma_f32_32x32x16_bf16 v[102:117], v[236:239], v[122:125], v[102:117]
	ds_read_b128 v[236:239], v207 offset:8800
	s_waitcnt lgkmcnt(7)
	v_mfma_f32_32x32x16_bf16 v[102:117], v[240:243], v[130:133], v[102:117]
	ds_read_b128 v[240:243], v207 offset:8832
	s_waitcnt lgkmcnt(7)
	v_mfma_f32_32x32x16_bf16 v[102:117], v[244:247], v[134:137], v[102:117]
	ds_read_b128 v[244:247], v207 offset:8864
	s_waitcnt lgkmcnt(7)
	v_mfma_f32_32x32x16_bf16 v[102:117], v[248:251], v[138:141], v[102:117]
	ds_read_b128 v[248:251], v207 offset:8896
	s_waitcnt lgkmcnt(7)
; #define LAS __attribute__((address_space(3)))
; __device__ __forceinline__ unsigned pk2(float lo, float hi) { f32x2_t v = {lo, hi}; bf16x2_t b = __builtin_convertvector(v, bf16x2_t); return __builtin_bit_cast(unsigned, b); }
; __device__ __forceinline__ f32x16 mfma32(bf16x8 a, bf16x8 b, f32x16 c) { return __builtin_amdgcn_mfma_f32_32x32x16_bf16(a, b, c, 0, 0, 0); }
; __device__ __forceinline__ void dsa_unit32(const Args& a, LAS unsigned char* lds, const LAS unsigned long long* maskl, int b, int qb, int tid, int wave, int lane) {
;     ...
;             for (int i = 0; i < 16; ++i) S2[kh][i] = negB;
;             __builtin_amdgcn_s_setprio(1);
; #pragma unroll
;             for (int ks = 0; ks < 8; ++ks) S2[kh] = mfma32(*(const LAS bf16x8*)(Ks + (32 * kh + l31) * KS + 16 * ks + 8 * hi), qf[ks], S2[kh]);
;             __builtin_amdgcn_s_setprio(0);
;         }
; #pragma unroll
;         for (int kh = 0; kh < 2; ++kh) {
;             const unsigned mh = (unsigned)(mw >> (32 * kh + 4 * hi));
;             float p[16];
; #pragma unroll
;             for (int i = 0; i < 16; ++i) { const float e = __builtin_amdgcn_exp2f(S2[kh][i]);
;                 const int keep = __builtin_amdgcn_sbfe((int)mh, 8 * (i >> 2) + (i & 3), 1);
;                 p[i] = __builtin_bit_cast(float, __builtin_bit_cast(int, e) & keep); l += p[i]; }
;             u32x4 w0, w1;
;             w0.x = pk2(p[0], p[1]); w0.y = pk2(p[2], p[3]); w0.z = pk2(p[4], p[5]); w0.w = pk2(p[6], p[7]);
	v_mfma_f32_32x32x16_bf16 v[102:117], v[222:225], v[142:145], v[102:117]
	ds_read_b128 v[222:225], v207 offset:8928
	s_setprio 0
	s_nop 7
	s_nop 3
	v_lshrrev_b64 v[208:209], v182, v[220:221]
	v_exp_f32_e32 v102, v102
	v_bfe_i32 v209, v208, 0, 1
	v_exp_f32_e32 v103, v103
	v_bfe_i32 v210, v208, 1, 1
	v_and_b32_e32 v102, v102, v209
	v_exp_f32_e32 v104, v104
	v_bfe_i32 v211, v208, 2, 1
	v_and_b32_e32 v103, v103, v210
	v_exp_f32_e32 v105, v105
	v_bfe_i32 v209, v208, 3, 1
	v_and_b32_e32 v104, v104, v211
	v_exp_f32_e32 v106, v106
	v_bfe_i32 v210, v208, 8, 1
	v_and_b32_e32 v105, v105, v209
	v_exp_f32_e32 v107, v107
	v_bfe_i32 v211, v208, 9, 1
	v_and_b32_e32 v106, v106, v210
	v_exp_f32_e32 v108, v108
	v_bfe_i32 v209, v208, 10, 1
	v_and_b32_e32 v107, v107, v211
	v_exp_f32_e32 v109, v109
	v_bfe_i32 v210, v208, 11, 1
	v_and_b32_e32 v108, v108, v209
	v_exp_f32_e32 v110, v110
	v_bfe_i32 v211, v208, 16, 1
	v_and_b32_e32 v109, v109, v210
	v_exp_f32_e32 v111, v111
	v_bfe_i32 v209, v208, 17, 1
	v_and_b32_e32 v110, v110, v211
	v_exp_f32_e32 v112, v112
	v_bfe_i32 v210, v208, 18, 1
	v_and_b32_e32 v111, v111, v209
	v_exp_f32_e32 v113, v113
	v_bfe_i32 v211, v208, 19, 1
	v_and_b32_e32 v112, v112, v210
	v_exp_f32_e32 v114, v114
	v_bfe_i32 v209, v208, 24, 1
	v_and_b32_e32 v113, v113, v211
	v_exp_f32_e32 v115, v115
	v_bfe_i32 v210, v208, 25, 1
	v_and_b32_e32 v114, v114, v209
	v_exp_f32_e32 v116, v116
	v_bfe_i32 v211, v208, 26, 1
	v_and_b32_e32 v115, v115, v210
	v_exp_f32_e32 v117, v117
	v_bfe_i32 v209, v208, 27, 1
	v_and_b32_e32 v116, v116, v211
	s_nop 0
	v_and_b32_e32 v117, v117, v209
	v_cvt_pk_bf16_f32 v208, v102, v103
	v_cvt_pk_bf16_f32 v209, v104, v105
	v_cvt_pk_bf16_f32 v210, v106, v107
	v_cvt_pk_bf16_f32 v211, v108, v109
	v_cvt_pk_bf16_f32 v212, v110, v111
	v_cvt_pk_bf16_f32 v213, v112, v113
	v_cvt_pk_bf16_f32 v214, v114, v115
	v_cvt_pk_bf16_f32 v215, v116, v117
	s_setprio 1
	s_waitcnt lgkmcnt(7)
	v_mfma_f32_32x32x16_bf16 v[86:101], v[216:219], v[126:129], v[70:85]
	v_add_u32_e32 v207, 17408, v203
	ds_read2_b64 v[216:219], v207 offset0:0 offset1:2
	s_waitcnt lgkmcnt(7)
	v_mfma_f32_32x32x16_bf16 v[86:101], v[228:231], v[0:3], v[86:101]
	ds_read2_b64 v[228:231], v207 offset0:4 offset1:6
	s_waitcnt lgkmcnt(7)
	v_mfma_f32_32x32x16_bf16 v[86:101], v[232:235], v[118:121], v[86:101]
	v_add_u32_e32 v207, 22272, v203
	ds_read2_b64 v[232:235], v207 offset0:0 offset1:2
	s_waitcnt lgkmcnt(7)
	v_mfma_f32_32x32x16_bf16 v[86:101], v[236:239], v[122:125], v[86:101]
	ds_read2_b64 v[236:239], v207 offset0:4 offset1:6
	s_waitcnt lgkmcnt(7)
	v_mfma_f32_32x32x16_bf16 v[86:101], v[240:243], v[130:133], v[86:101]
	v_add_u32_e32 v207, 27136, v203
	ds_read2_b64 v[240:243], v207 offset0:0 offset1:2
	s_waitcnt lgkmcnt(7)
	v_mfma_f32_32x32x16_bf16 v[86:101], v[244:247], v[134:137], v[86:101]
	ds_read2_b64 v[244:247], v207 offset0:4 offset1:6
	s_waitcnt lgkmcnt(7)
	v_mfma_f32_32x32x16_bf16 v[86:101], v[248:251], v[138:141], v[86:101]
	v_add_u32_e32 v207, 32000, v203
	ds_read2_b64 v[248:251], v207 offset0:0 offset1:2
	s_waitcnt lgkmcnt(7)
; #define LAS __attribute__((address_space(3)))
; __device__ __forceinline__ unsigned pk2(float lo, float hi) { f32x2_t v = {lo, hi}; bf16x2_t b = __builtin_convertvector(v, bf16x2_t); return __builtin_bit_cast(unsigned, b); }
; __device__ __forceinline__ f32x16 mfma32(bf16x8 a, bf16x8 b, f32x16 c) { return __builtin_amdgcn_mfma_f32_32x32x16_bf16(a, b, c, 0, 0, 0); }
; __device__ __forceinline__ void dsa_unit32(const Args& a, LAS unsigned char* lds, const LAS unsigned long long* maskl, int b, int qb, int tid, int wave, int lane) {
;     ...
;         for (int kh = 0; kh < 2; ++kh) {
;             const unsigned mh = (unsigned)(mw >> (32 * kh + 4 * hi));
;             float p[16];
; #pragma unroll
;             for (int i = 0; i < 16; ++i) { const float e = __builtin_amdgcn_exp2f(S2[kh][i]);
;                 const int keep = __builtin_amdgcn_sbfe((int)mh, 8 * (i >> 2) + (i & 3), 1);
;                 p[i] = __builtin_bit_cast(float, __builtin_bit_cast(int, e) & keep); l += p[i]; }
;             u32x4 w0, w1;
;             w0.x = pk2(p[0], p[1]); w0.y = pk2(p[2], p[3]); w0.z = pk2(p[4], p[5]); w0.w = pk2(p[6], p[7]);
;             w1.x = pk2(p[8], p[9]); w1.y = pk2(p[10], p[11]); w1.z = pk2(p[12], p[13]); w1.w = pk2(p[14], p[15]);
;             const bf16x8 pa = __builtin_bit_cast(bf16x8, w0), pb = __builtin_bit_cast(bf16x8, w1);
;             __builtin_amdgcn_s_setprio(1);
; #pragma unroll
;             for (int ct = 0; ct < 4; ++ct) {
;                 const LAS bf16* vr = Vs + (32 * ct + l31) * VS + 4 * hi + 32 * kh;
;                 O[ct] = mfma32(cat8(*(const LAS u32x2*)(vr), *(const LAS u32x2*)(vr + 8)), pa, O[ct]);
;                 O[ct] = mfma32(cat8(*(const LAS u32x2*)(vr + 16), *(const LAS u32x2*)(vr + 24)), pb, O[ct]);
;             }
;             __builtin_amdgcn_s_setprio(0);
;         }
	v_mfma_f32_32x32x16_bf16 v[86:101], v[222:225], v[142:145], v[86:101]
	ds_read2_b64 v[222:225], v207 offset0:4 offset1:6
	s_setprio 0
	v_add_f32_e32 v194, v194, v102
	v_add_f32_e32 v194, v103, v194
	v_add_f32_e32 v194, v104, v194
	v_add_f32_e32 v194, v105, v194
	v_add_f32_e32 v194, v106, v194
	v_add_f32_e32 v194, v107, v194
	v_add_f32_e32 v194, v108, v194
	v_add_f32_e32 v194, v109, v194
	v_add_f32_e32 v194, v110, v194
	v_add_f32_e32 v194, v111, v194
	v_add_f32_e32 v194, v112, v194
	v_add_f32_e32 v194, v113, v194
	v_add_f32_e32 v194, v114, v194
	v_add_f32_e32 v194, v115, v194
	v_add_f32_e32 v194, v116, v194
	v_add_f32_e32 v194, v117, v194
	v_lshrrev_b64 v[110:111], v184, v[220:221]
	v_exp_f32_e32 v86, v86
	v_bfe_i32 v111, v110, 0, 1
	v_exp_f32_e32 v87, v87
	v_bfe_i32 v112, v110, 1, 1
	v_and_b32_e32 v86, v86, v111
	v_exp_f32_e32 v88, v88
	v_bfe_i32 v113, v110, 2, 1
	v_and_b32_e32 v87, v87, v112
	v_exp_f32_e32 v89, v89
	v_bfe_i32 v111, v110, 3, 1
	v_and_b32_e32 v88, v88, v113
	v_exp_f32_e32 v90, v90
	v_bfe_i32 v112, v110, 8, 1
	v_and_b32_e32 v89, v89, v111
	v_exp_f32_e32 v91, v91
	v_bfe_i32 v113, v110, 9, 1
	v_and_b32_e32 v90, v90, v112
	v_exp_f32_e32 v92, v92
	v_bfe_i32 v111, v110, 10, 1
	v_and_b32_e32 v91, v91, v113
	v_exp_f32_e32 v93, v93
	v_bfe_i32 v112, v110, 11, 1
	v_and_b32_e32 v92, v92, v111
	v_exp_f32_e32 v94, v94
	v_bfe_i32 v113, v110, 16, 1
	v_and_b32_e32 v93, v93, v112
	v_exp_f32_e32 v95, v95
	v_bfe_i32 v111, v110, 17, 1
	v_and_b32_e32 v94, v94, v113
	v_exp_f32_e32 v96, v96
	v_bfe_i32 v112, v110, 18, 1
	v_and_b32_e32 v95, v95, v111
	v_exp_f32_e32 v97, v97
	v_bfe_i32 v113, v110, 19, 1
	v_and_b32_e32 v96, v96, v112
	v_exp_f32_e32 v98, v98
	v_bfe_i32 v111, v110, 24, 1
	v_and_b32_e32 v97, v97, v113
	v_exp_f32_e32 v99, v99
	v_bfe_i32 v112, v110, 25, 1
	v_and_b32_e32 v98, v98, v111
	v_exp_f32_e32 v100, v100
	v_bfe_i32 v113, v110, 26, 1
	v_and_b32_e32 v99, v99, v112
	v_exp_f32_e32 v101, v101
	v_bfe_i32 v111, v110, 27, 1
	v_and_b32_e32 v100, v100, v113
	s_nop 0
	v_and_b32_e32 v101, v101, v111
	v_cvt_pk_bf16_f32 v102, v86, v87
	v_cvt_pk_bf16_f32 v103, v88, v89
	v_cvt_pk_bf16_f32 v104, v90, v91
	v_cvt_pk_bf16_f32 v105, v92, v93
	v_cvt_pk_bf16_f32 v106, v94, v95
	v_cvt_pk_bf16_f32 v107, v96, v97
	v_cvt_pk_bf16_f32 v108, v98, v99
	v_cvt_pk_bf16_f32 v109, v100, v101
	s_nop 1
	s_setprio 1
	s_waitcnt lgkmcnt(7)
	v_mfma_f32_32x32x16_bf16 v[54:69], v[216:219], v[208:211], v[54:69]
	v_add_u32_e32 v207, 17408, v203
	ds_read2_b64 v[216:219], v207 offset0:8 offset1:10
	s_waitcnt lgkmcnt(7)
	v_mfma_f32_32x32x16_bf16 v[54:69], v[228:231], v[212:215], v[54:69]
	ds_read2_b64 v[228:231], v207 offset0:12 offset1:14
	s_waitcnt lgkmcnt(7)
	v_mfma_f32_32x32x16_bf16 v[38:53], v[232:235], v[208:211], v[38:53]
	v_add_u32_e32 v207, 22272, v203
	ds_read2_b64 v[232:235], v207 offset0:8 offset1:10
	s_waitcnt lgkmcnt(7)
	v_mfma_f32_32x32x16_bf16 v[38:53], v[236:239], v[212:215], v[38:53]
	ds_read2_b64 v[236:239], v207 offset0:12 offset1:14
	s_waitcnt lgkmcnt(7)
	v_mfma_f32_32x32x16_bf16 v[22:37], v[240:243], v[208:211], v[22:37]
	v_add_u32_e32 v207, 27136, v203
	ds_read2_b64 v[240:243], v207 offset0:8 offset1:10
	s_waitcnt lgkmcnt(7)
	v_mfma_f32_32x32x16_bf16 v[22:37], v[244:247], v[212:215], v[22:37]
	ds_read2_b64 v[244:247], v207 offset0:12 offset1:14
	s_waitcnt lgkmcnt(7)
	v_mfma_f32_32x32x16_bf16 v[6:21], v[248:251], v[208:211], v[6:21]
	v_add_u32_e32 v207, 32000, v203
	ds_read2_b64 v[248:251], v207 offset0:8 offset1:10
	s_waitcnt lgkmcnt(7)
	v_mfma_f32_32x32x16_bf16 v[6:21], v[222:225], v[212:215], v[6:21]
	ds_read2_b64 v[222:225], v207 offset0:12 offset1:14
	s_waitcnt lgkmcnt(7)
	v_mfma_f32_32x32x16_bf16 v[54:69], v[216:219], v[102:105], v[54:69]
	v_add_f32_e32 v194, v194, v86
	v_add_f32_e32 v194, v87, v194
	s_waitcnt lgkmcnt(6)
	v_mfma_f32_32x32x16_bf16 v[54:69], v[228:231], v[106:109], v[54:69]
	v_add_f32_e32 v194, v88, v194
	v_add_f32_e32 v194, v89, v194
	s_waitcnt lgkmcnt(5)
	v_mfma_f32_32x32x16_bf16 v[38:53], v[232:235], v[102:105], v[38:53]
	v_add_f32_e32 v194, v90, v194
	v_add_f32_e32 v194, v91, v194
	s_waitcnt lgkmcnt(4)
	v_mfma_f32_32x32x16_bf16 v[38:53], v[236:239], v[106:109], v[38:53]
	v_add_f32_e32 v194, v92, v194
	v_add_f32_e32 v194, v93, v194
	s_waitcnt lgkmcnt(3)
	v_mfma_f32_32x32x16_bf16 v[22:37], v[240:243], v[102:105], v[22:37]
	v_add_f32_e32 v194, v94, v194
	v_add_f32_e32 v194, v95, v194
	s_waitcnt lgkmcnt(2)
	v_mfma_f32_32x32x16_bf16 v[22:37], v[244:247], v[106:109], v[22:37]
	v_add_f32_e32 v194, v96, v194
	v_add_f32_e32 v194, v97, v194
	s_waitcnt lgkmcnt(1)
	v_mfma_f32_32x32x16_bf16 v[6:21], v[248:251], v[102:105], v[6:21]
	v_add_f32_e32 v194, v98, v194
	v_add_f32_e32 v194, v99, v194
	s_waitcnt lgkmcnt(0)
	v_mfma_f32_32x32x16_bf16 v[6:21], v[222:225], v[106:109], v[6:21]
	v_add_f32_e32 v194, v100, v194
	v_add_f32_e32 v194, v101, v194
	s_setprio 0
.Ldsa_J0:
	s_add_i32 s7, s5, -2
	s_cmp_lt_u32 s7, s4
	s_cselect_b64 s[2:3], -1, 0
	s_cmp_ge_u32 s7, s4
	s_cbranch_scc1 .LBB0_1306
	s_mov_b32 s7, 0xd400
	v_add3_u32 v208, v195, v197, s7
	s_waitcnt vmcnt(3)
	ds_write_b128 v196, v[162:165] offset:36864
	s_waitcnt vmcnt(1)
	ds_write2_b64 v208, v[170:171], v[172:173] offset1:1
	ds_write_b128 v199, v[166:169] offset:36864
	v_add3_u32 v208, v195, v200, s7
	s_waitcnt vmcnt(0)
	ds_write2_b64 v208, v[174:175], v[176:177] offset1:1

; #define LAS __attribute__((address_space(3)))
; __device__ __forceinline__ f32x16 mfma32(bf16x8 a, bf16x8 b, f32x16 c) { return __builtin_amdgcn_mfma_f32_32x32x16_bf16(a, b, c, 0, 0, 0); }
; __device__ __forceinline__ void dsa_unit32(const Args& a, LAS unsigned char* lds, const LAS unsigned long long* maskl, int b, int qb, int tid, int wave, int lane) {
;     ...
;         const unsigned long long mw = maskl[l31 * 32 + kt];
;         const LAS bf16* Ks = (const LAS bf16*)(lds + buf * STG); const LAS bf16* Vs = (const LAS bf16*)(lds + buf * STG + KBYTES);
;         f32x16 S2[2];
; #pragma unroll
;         for (int kh = 0; kh < 2; ++kh) {
; #pragma unroll
;             for (int i = 0; i < 16; ++i) S2[kh][i] = negB;
;             __builtin_amdgcn_s_setprio(1);
; #pragma unroll
;             for (int ks = 0; ks < 8; ++ks) S2[kh] = mfma32(*(const LAS bf16x8*)(Ks + (32 * kh + l31) * KS + 16 * ks + 8 * hi), qf[ks], S2[kh]);
;             __builtin_amdgcn_s_setprio(0);
;         }
; #pragma unroll
;         for (int kh = 0; kh < 2; ++kh) {
;             const unsigned mh = (unsigned)(mw >> (32 * kh + 4 * hi));
;             float p[16];
; #pragma unroll
;             for (int i = 0; i < 16; ++i) { const float e = __builtin_amdgcn_exp2f(S2[kh][i]);
;                 const int keep = __builtin_amdgcn_sbfe((int)mh, 8 * (i >> 2) + (i & 3), 1);
;                 p[i] = __builtin_bit_cast(float, __builtin_bit_cast(int, e) & keep); l += p[i]; }
.LBB0_1309:
	s_cmp_lt_u32 s17, 4
	s_cbranch_scc0 .Ldsa_B1
	ds_read_b64 v[220:221], v206
	v_add_u32_e32 v207, v202, v180
	ds_read_b128 v[216:219], v207 offset:36864
	ds_read_b128 v[228:231], v207 offset:36896
	ds_read_b128 v[232:235], v207 offset:36928
	ds_read_b128 v[236:239], v207 offset:36960
	ds_read_b128 v[240:243], v207 offset:36992
	ds_read_b128 v[244:247], v207 offset:37024
	ds_read_b128 v[248:251], v207 offset:37056
	ds_read_b128 v[222:225], v207 offset:37088
	ds_read_b128 v[208:211], v207 offset:45568
	ds_read_b128 v[212:215], v207 offset:45600
	s_setprio 1
	s_waitcnt lgkmcnt(9)
	v_mfma_f32_32x32x16_bf16 v[102:117], v[216:219], v[126:129], v[70:85]
	ds_read_b128 v[216:219], v207 offset:45632
	s_waitcnt lgkmcnt(9)
	v_mfma_f32_32x32x16_bf16 v[102:117], v[228:231], v[0:3], v[102:117]
	ds_read_b128 v[228:231], v207 offset:45664
	s_waitcnt lgkmcnt(9)
	v_mfma_f32_32x32x16_bf16 v[102:117], v[232:235], v[118:121], v[102:117]
	ds_read_b128 v[232:235], v207 offset:45696
	s_waitcnt lgkmcnt(9)
	v_mfma_f32_32x32x16_bf16 v[102:117], v[236:239], v[122:125], v[102:117]
	ds_read_b128 v[236:239], v207 offset:45728
	s_waitcnt lgkmcnt(9)
	v_mfma_f32_32x32x16_bf16 v[102:117], v[240:243], v[130:133], v[102:117]
	ds_read_b128 v[240:243], v207 offset:45760
	s_waitcnt lgkmcnt(9)
	v_mfma_f32_32x32x16_bf16 v[102:117], v[244:247], v[134:137], v[102:117]
	ds_read_b128 v[244:247], v207 offset:45792
	s_waitcnt lgkmcnt(9)
	v_mfma_f32_32x32x16_bf16 v[102:117], v[248:251], v[138:141], v[102:117]
	s_waitcnt lgkmcnt(8)
	v_mfma_f32_32x32x16_bf16 v[102:117], v[222:225], v[142:145], v[102:117]
	s_waitcnt lgkmcnt(7)
	v_mfma_f32_32x32x16_bf16 v[86:101], v[208:211], v[126:129], v[70:85]
	s_waitcnt lgkmcnt(6)
	v_mfma_f32_32x32x16_bf16 v[86:101], v[212:215], v[0:3], v[86:101]
	s_waitcnt lgkmcnt(5)
	v_mfma_f32_32x32x16_bf16 v[86:101], v[216:219], v[118:121], v[86:101]
	ds_read2_b64 v[248:251], v204 offset0:0 offset1:2
	ds_read2_b64 v[222:225], v204 offset0:4 offset1:6
	v_add_u32_e32 v207, 4864, v204
	ds_read2_b64 v[216:219], v207 offset0:0 offset1:2
	s_waitcnt lgkmcnt(7)
	v_mfma_f32_32x32x16_bf16 v[86:101], v[228:231], v[122:125], v[86:101]
	ds_read2_b64 v[228:231], v207 offset0:4 offset1:6
	s_waitcnt lgkmcnt(7)
	v_mfma_f32_32x32x16_bf16 v[86:101], v[232:235], v[130:133], v[86:101]
	v_add_u32_e32 v207, 9728, v204
	ds_read2_b64 v[232:235], v207 offset0:0 offset1:2
	s_waitcnt lgkmcnt(7)
	v_mfma_f32_32x32x16_bf16 v[86:101], v[236:239], v[134:137], v[86:101]
	ds_read2_b64 v[236:239], v207 offset0:4 offset1:6
	s_waitcnt lgkmcnt(7)
	v_mfma_f32_32x32x16_bf16 v[86:101], v[240:243], v[138:141], v[86:101]
	v_add_u32_e32 v207, 14592, v204
	ds_read2_b64 v[240:243], v207 offset0:0 offset1:2
	s_waitcnt lgkmcnt(7)
	v_mfma_f32_32x32x16_bf16 v[86:101], v[244:247], v[142:145], v[86:101]
	ds_read2_b64 v[244:247], v207 offset0:4 offset1:6
	s_setprio 0
	v_lshrrev_b64 v[208:209], v182, v[220:221]
	v_exp_f32_e32 v102, v102
	v_bfe_i32 v209, v208, 0, 1
	v_exp_f32_e32 v103, v103
	v_bfe_i32 v210, v208, 1, 1
	v_and_b32_e32 v102, v102, v209
	v_exp_f32_e32 v104, v104
	v_bfe_i32 v211, v208, 2, 1
	v_and_b32_e32 v103, v103, v210
	v_exp_f32_e32 v105, v105
	v_bfe_i32 v209, v208, 3, 1
	v_and_b32_e32 v104, v104, v211
	v_exp_f32_e32 v106, v106
	v_bfe_i32 v210, v208, 8, 1
	v_and_b32_e32 v105, v105, v209
	v_exp_f32_e32 v107, v107
	v_bfe_i32 v211, v208, 9, 1
	v_and_b32_e32 v106, v106, v210
	v_exp_f32_e32 v108, v108
	v_bfe_i32 v209, v208, 10, 1
	v_and_b32_e32 v107, v107, v211
	v_exp_f32_e32 v109, v109
	v_bfe_i32 v210, v208, 11, 1
	v_and_b32_e32 v108, v108, v209
	v_exp_f32_e32 v110, v110
	v_bfe_i32 v211, v208, 16, 1
	v_and_b32_e32 v109, v109, v210
	v_exp_f32_e32 v111, v111
	v_bfe_i32 v209, v208, 17, 1
	v_and_b32_e32 v110, v110, v211
	v_exp_f32_e32 v112, v112
	v_bfe_i32 v210, v208, 18, 1
	v_and_b32_e32 v111, v111, v209
	v_exp_f32_e32 v113, v113
	v_bfe_i32 v211, v208, 19, 1
	v_and_b32_e32 v112, v112, v210
	v_exp_f32_e32 v114, v114
	v_bfe_i32 v209, v208, 24, 1
	v_and_b32_e32 v113, v113, v211
	v_exp_f32_e32 v115, v115
	v_bfe_i32 v210, v208, 25, 1
	v_and_b32_e32 v114, v114, v209
	v_exp_f32_e32 v116, v116
	v_bfe_i32 v211, v208, 26, 1
	v_and_b32_e32 v115, v115, v210
	v_exp_f32_e32 v117, v117
	v_bfe_i32 v209, v208, 27, 1
	v_and_b32_e32 v116, v116, v211
	s_nop 0
	v_and_b32_e32 v117, v117, v209
	v_cvt_pk_bf16_f32 v208, v102, v103
	v_cvt_pk_bf16_f32 v209, v104, v105
	v_cvt_pk_bf16_f32 v210, v106, v107
	v_cvt_pk_bf16_f32 v211, v108, v109
	v_cvt_pk_bf16_f32 v212, v110, v111
	v_cvt_pk_bf16_f32 v213, v112, v113
	v_cvt_pk_bf16_f32 v214, v114, v115
	v_cvt_pk_bf16_f32 v215, v116, v117
	s_nop 1
	s_setprio 1
	s_waitcnt lgkmcnt(7)
	v_mfma_f32_32x32x16_bf16 v[54:69], v[248:251], v[208:211], v[54:69]
	ds_read2_b64 v[248:251], v204 offset0:8 offset1:10
	v_add_f32_e32 v194, v194, v102
	v_add_f32_e32 v194, v103, v194
	s_waitcnt lgkmcnt(7)
	v_mfma_f32_32x32x16_bf16 v[54:69], v[222:225], v[212:215], v[54:69]
	ds_read2_b64 v[222:225], v204 offset0:12 offset1:14
	v_add_f32_e32 v194, v104, v194
	v_add_f32_e32 v194, v105, v194
	s_waitcnt lgkmcnt(7)
	v_mfma_f32_32x32x16_bf16 v[38:53], v[216:219], v[208:211], v[38:53]
	v_add_u32_e32 v207, 4864, v204
	ds_read2_b64 v[216:219], v207 offset0:8 offset1:10
	v_add_f32_e32 v194, v106, v194
	v_add_f32_e32 v194, v107, v194
	s_waitcnt lgkmcnt(7)
	v_mfma_f32_32x32x16_bf16 v[38:53], v[228:231], v[212:215], v[38:53]
	ds_read2_b64 v[228:231], v207 offset0:12 offset1:14
	v_add_f32_e32 v194, v108, v194
	v_add_f32_e32 v194, v109, v194
	s_waitcnt lgkmcnt(7)
	v_mfma_f32_32x32x16_bf16 v[22:37], v[232:235], v[208:211], v[22:37]
	v_add_u32_e32 v207, 9728, v204
	ds_read2_b64 v[232:235], v207 offset0:8 offset1:10
	v_add_f32_e32 v194, v110, v194
	v_add_f32_e32 v194, v111, v194
	s_waitcnt lgkmcnt(7)
; #define LAS __attribute__((address_space(3)))
; __device__ __forceinline__ unsigned pk2(float lo, float hi) { f32x2_t v = {lo, hi}; bf16x2_t b = __builtin_convertvector(v, bf16x2_t); return __builtin_bit_cast(unsigned, b); }
; __device__ __forceinline__ void dsa_unit32(const Args& a, LAS unsigned char* lds, const LAS unsigned long long* maskl, int b, int qb, int tid, int wave, int lane) {
;     ...
;         const unsigned long long mw = maskl[l31 * 32 + kt];
;         const LAS bf16* Ks = (const LAS bf16*)(lds + buf * STG); const LAS bf16* Vs = (const LAS bf16*)(lds + buf * STG + KBYTES);
;         f32x16 S2[2];
; #pragma unroll
;         for (int kh = 0; kh < 2; ++kh) {
; #pragma unroll
;             for (int i = 0; i < 16; ++i) S2[kh][i] = negB;
;             __builtin_amdgcn_s_setprio(1);
; #pragma unroll
;             for (int ks = 0; ks < 8; ++ks) S2[kh] = mfma32(*(const LAS bf16x8*)(Ks + (32 * kh + l31) * KS + 16 * ks + 8 * hi), qf[ks], S2[kh]);
;             __builtin_amdgcn_s_setprio(0);
;     ...
;         for (int kh = 0; kh < 2; ++kh) {
;             const unsigned mh = (unsigned)(mw >> (32 * kh + 4 * hi));
;             float p[16];
; #pragma unroll
;             for (int i = 0; i < 16; ++i) { const float e = __builtin_amdgcn_exp2f(S2[kh][i]);
;                 const int keep = __builtin_amdgcn_sbfe((int)mh, 8 * (i >> 2) + (i & 3), 1);
;                 p[i] = __builtin_bit_cast(float, __builtin_bit_cast(int, e) & keep); l += p[i]; }
;             u32x4 w0, w1;
;             w0.x = pk2(p[0], p[1]); w0.y = pk2(p[2], p[3]); w0.z = pk2(p[4], p[5]); w0.w = pk2(p[6], p[7]);
;             w1.x = pk2(p[8], p[9]); w1.y = pk2(p[10], p[11]); w1.z = pk2(p[12], p[13]); w1.w = pk2(p[14], p[15]);
;             const bf16x8 pa = __builtin_bit_cast(bf16x8, w0), pb = __builtin_bit_cast(bf16x8, w1);
;             __builtin_amdgcn_s_setprio(1);
; #pragma unroll
;             for (int ct = 0; ct < 4; ++ct) {
;                 const LAS bf16* vr = Vs + (32 * ct + l31) * VS + 4 * hi + 32 * kh;
;                 O[ct] = mfma32(cat8(*(const LAS u32x2*)(vr), *(const LAS u32x2*)(vr + 8)), pa, O[ct]);
;                 O[ct] = mfma32(cat8(*(const LAS u32x2*)(vr + 16), *(const LAS u32x2*)(vr + 24)), pb, O[ct]);
;             }
;             __builtin_amdgcn_s_setprio(0);
;         }
	v_mfma_f32_32x32x16_bf16 v[22:37], v[236:239], v[212:215], v[22:37]
	ds_read2_b64 v[236:239], v207 offset0:12 offset1:14
	v_add_f32_e32 v194, v112, v194
	v_add_f32_e32 v194, v113, v194
	s_waitcnt lgkmcnt(7)
	v_mfma_f32_32x32x16_bf16 v[6:21], v[240:243], v[208:211], v[6:21]
	v_add_u32_e32 v207, 14592, v204
	ds_read2_b64 v[240:243], v207 offset0:8 offset1:10
	v_add_f32_e32 v194, v114, v194
	v_add_f32_e32 v194, v115, v194
	s_waitcnt lgkmcnt(7)
	v_mfma_f32_32x32x16_bf16 v[6:21], v[244:247], v[212:215], v[6:21]
	ds_read2_b64 v[244:247], v207 offset0:12 offset1:14
	v_add_f32_e32 v194, v116, v194
	v_add_f32_e32 v194, v117, v194
	s_setprio 0
	v_lshrrev_b64 v[208:209], v184, v[220:221]
	v_exp_f32_e32 v86, v86
	v_bfe_i32 v209, v208, 0, 1
	v_exp_f32_e32 v87, v87
	v_bfe_i32 v210, v208, 1, 1
	v_and_b32_e32 v86, v86, v209
	v_exp_f32_e32 v88, v88
	v_bfe_i32 v211, v208, 2, 1
	v_and_b32_e32 v87, v87, v210
	v_exp_f32_e32 v89, v89
	v_bfe_i32 v209, v208, 3, 1
	v_and_b32_e32 v88, v88, v211
	v_exp_f32_e32 v90, v90
	v_bfe_i32 v210, v208, 8, 1
	v_and_b32_e32 v89, v89, v209
	v_exp_f32_e32 v91, v91
	v_bfe_i32 v211, v208, 9, 1
	v_and_b32_e32 v90, v90, v210
	v_exp_f32_e32 v92, v92
	v_bfe_i32 v209, v208, 10, 1
	v_and_b32_e32 v91, v91, v211
	v_exp_f32_e32 v93, v93
	v_bfe_i32 v210, v208, 11, 1
	v_and_b32_e32 v92, v92, v209
	v_exp_f32_e32 v94, v94
	v_bfe_i32 v211, v208, 16, 1
	v_and_b32_e32 v93, v93, v210
	v_exp_f32_e32 v95, v95
	v_bfe_i32 v209, v208, 17, 1
	v_and_b32_e32 v94, v94, v211
	v_exp_f32_e32 v96, v96
	v_bfe_i32 v210, v208, 18, 1
	v_and_b32_e32 v95, v95, v209
	v_exp_f32_e32 v97, v97
	v_bfe_i32 v211, v208, 19, 1
	v_and_b32_e32 v96, v96, v210
	v_exp_f32_e32 v98, v98
	v_bfe_i32 v209, v208, 24, 1
	v_and_b32_e32 v97, v97, v211
	v_exp_f32_e32 v99, v99
	v_bfe_i32 v210, v208, 25, 1
	v_and_b32_e32 v98, v98, v209
	v_exp_f32_e32 v100, v100
	v_bfe_i32 v211, v208, 26, 1
	v_and_b32_e32 v99, v99, v210
	v_exp_f32_e32 v101, v101
	v_bfe_i32 v209, v208, 27, 1
	v_and_b32_e32 v100, v100, v211
	s_nop 0
	v_and_b32_e32 v101, v101, v209
	v_cvt_pk_bf16_f32 v208, v86, v87
	v_cvt_pk_bf16_f32 v209, v88, v89
	v_cvt_pk_bf16_f32 v210, v90, v91
	v_cvt_pk_bf16_f32 v211, v92, v93
	v_cvt_pk_bf16_f32 v212, v94, v95
	v_cvt_pk_bf16_f32 v213, v96, v97
	v_cvt_pk_bf16_f32 v214, v98, v99
	v_cvt_pk_bf16_f32 v215, v100, v101
	s_nop 1
	s_setprio 1
	s_waitcnt lgkmcnt(7)
	v_mfma_f32_32x32x16_bf16 v[54:69], v[248:251], v[208:211], v[54:69]
	v_add_f32_e32 v194, v194, v86
	v_add_f32_e32 v194, v87, v194
	s_waitcnt lgkmcnt(6)
	v_mfma_f32_32x32x16_bf16 v[54:69], v[222:225], v[212:215], v[54:69]
	v_add_f32_e32 v194, v88, v194
	v_add_f32_e32 v194, v89, v194
	s_waitcnt lgkmcnt(5)
	v_mfma_f32_32x32x16_bf16 v[38:53], v[216:219], v[208:211], v[38:53]
	v_add_f32_e32 v194, v90, v194
	v_add_f32_e32 v194, v91, v194
	s_waitcnt lgkmcnt(4)
	v_mfma_f32_32x32x16_bf16 v[38:53], v[228:231], v[212:215], v[38:53]
	v_add_f32_e32 v194, v92, v194
	v_add_f32_e32 v194, v93, v194
	s_waitcnt lgkmcnt(3)
	v_mfma_f32_32x32x16_bf16 v[22:37], v[232:235], v[208:211], v[22:37]
	v_add_f32_e32 v194, v94, v194
	v_add_f32_e32 v194, v95, v194
	s_waitcnt lgkmcnt(2)
	v_mfma_f32_32x32x16_bf16 v[22:37], v[236:239], v[212:215], v[22:37]
	v_add_f32_e32 v194, v96, v194
	v_add_f32_e32 v194, v97, v194
	s_waitcnt lgkmcnt(1)
	v_mfma_f32_32x32x16_bf16 v[6:21], v[240:243], v[208:211], v[6:21]
	v_add_f32_e32 v194, v98, v194
	v_add_f32_e32 v194, v99, v194
	s_waitcnt lgkmcnt(0)
	v_mfma_f32_32x32x16_bf16 v[6:21], v[244:247], v[212:215], v[6:21]
	v_add_f32_e32 v194, v100, v194
	v_add_f32_e32 v194, v101, v194
	s_setprio 0
	s_branch .Ldsa_J1
.Ldsa_B1:
	ds_read_b64 v[220:221], v206
	v_add_u32_e32 v207, v202, v180
	ds_read_b128 v[216:219], v207 offset:36864
	ds_read_b128 v[228:231], v207 offset:36896
	ds_read_b128 v[232:235], v207 offset:36928
	ds_read_b128 v[236:239], v207 offset:36960
	ds_read_b128 v[240:243], v207 offset:36992
	ds_read_b128 v[244:247], v207 offset:37024
	ds_read_b128 v[248:251], v207 offset:37056
	ds_read_b128 v[222:225], v207 offset:37088
	s_setprio 1
	s_waitcnt lgkmcnt(7)
	v_mfma_f32_32x32x16_bf16 v[102:117], v[216:219], v[126:129], v[70:85]
	ds_read_b128 v[216:219], v207 offset:45568
	s_waitcnt lgkmcnt(7)
	v_mfma_f32_32x32x16_bf16 v[102:117], v[228:231], v[0:3], v[102:117]
	ds_read_b128 v[228:231], v207 offset:45600
	s_waitcnt lgkmcnt(7)
	v_mfma_f32_32x32x16_bf16 v[102:117], v[232:235], v[118:121], v[102:117]
	ds_read_b128 v[232:235], v207 offset:45632
	s_waitcnt lgkmcnt(7)
	v_mfma_f32_32x32x16_bf16 v[102:117], v[236:239], v[122:125], v[102:117]
	ds_read_b128 v[236:239], v207 offset:45664
	s_waitcnt lgkmcnt(7)
	v_mfma_f32_32x32x16_bf16 v[102:117], v[240:243], v[130:133], v[102:117]
	ds_read_b128 v[240:243], v207 offset:45696
	s_waitcnt lgkmcnt(7)
	v_mfma_f32_32x32x16_bf16 v[102:117], v[244:247], v[134:137], v[102:117]
	ds_read_b128 v[244:247], v207 offset:45728
	s_waitcnt lgkmcnt(7)
	v_mfma_f32_32x32x16_bf16 v[102:117], v[248:251], v[138:141], v[102:117]
	ds_read_b128 v[248:251], v207 offset:45760
	s_waitcnt lgkmcnt(7)
; #define LAS __attribute__((address_space(3)))
; __device__ __forceinline__ unsigned pk2(float lo, float hi) { f32x2_t v = {lo, hi}; bf16x2_t b = __builtin_convertvector(v, bf16x2_t); return __builtin_bit_cast(unsigned, b); }
; __device__ __forceinline__ f32x16 mfma32(bf16x8 a, bf16x8 b, f32x16 c) { return __builtin_amdgcn_mfma_f32_32x32x16_bf16(a, b, c, 0, 0, 0); }
; __device__ __forceinline__ void dsa_unit32(const Args& a, LAS unsigned char* lds, const LAS unsigned long long* maskl, int b, int qb, int tid, int wave, int lane) {
;     ...
;             for (int i = 0; i < 16; ++i) S2[kh][i] = negB;
;             __builtin_amdgcn_s_setprio(1);
; #pragma unroll
;             for (int ks = 0; ks < 8; ++ks) S2[kh] = mfma32(*(const LAS bf16x8*)(Ks + (32 * kh + l31) * KS + 16 * ks + 8 * hi), qf[ks], S2[kh]);
;             __builtin_amdgcn_s_setprio(0);
;         }
; #pragma unroll
;         for (int kh = 0; kh < 2; ++kh) {
;             const unsigned mh = (unsigned)(mw >> (32 * kh + 4 * hi));
;             float p[16];
; #pragma unroll
;             for (int i = 0; i < 16; ++i) { const float e = __builtin_amdgcn_exp2f(S2[kh][i]);
;                 const int keep = __builtin_amdgcn_sbfe((int)mh, 8 * (i >> 2) + (i & 3), 1);
;                 p[i] = __builtin_bit_cast(float, __builtin_bit_cast(int, e) & keep); l += p[i]; }
;             u32x4 w0, w1;
;             w0.x = pk2(p[0], p[1]); w0.y = pk2(p[2], p[3]); w0.z = pk2(p[4], p[5]); w0.w = pk2(p[6], p[7]);
	v_mfma_f32_32x32x16_bf16 v[102:117], v[222:225], v[142:145], v[102:117]
	ds_read_b128 v[222:225], v207 offset:45792
	s_setprio 0
	s_nop 7
	s_nop 3
	v_lshrrev_b64 v[208:209], v182, v[220:221]
	v_exp_f32_e32 v102, v102
	v_bfe_i32 v209, v208, 0, 1
	v_exp_f32_e32 v103, v103
	v_bfe_i32 v210, v208, 1, 1
	v_and_b32_e32 v102, v102, v209
	v_exp_f32_e32 v104, v104
	v_bfe_i32 v211, v208, 2, 1
	v_and_b32_e32 v103, v103, v210
	v_exp_f32_e32 v105, v105
	v_bfe_i32 v209, v208, 3, 1
	v_and_b32_e32 v104, v104, v211
	v_exp_f32_e32 v106, v106
	v_bfe_i32 v210, v208, 8, 1
	v_and_b32_e32 v105, v105, v209
	v_exp_f32_e32 v107, v107
	v_bfe_i32 v211, v208, 9, 1
	v_and_b32_e32 v106, v106, v210
	v_exp_f32_e32 v108, v108
	v_bfe_i32 v209, v208, 10, 1
	v_and_b32_e32 v107, v107, v211
	v_exp_f32_e32 v109, v109
	v_bfe_i32 v210, v208, 11, 1
	v_and_b32_e32 v108, v108, v209
	v_exp_f32_e32 v110, v110
	v_bfe_i32 v211, v208, 16, 1
	v_and_b32_e32 v109, v109, v210
	v_exp_f32_e32 v111, v111
	v_bfe_i32 v209, v208, 17, 1
	v_and_b32_e32 v110, v110, v211
	v_exp_f32_e32 v112, v112
	v_bfe_i32 v210, v208, 18, 1
	v_and_b32_e32 v111, v111, v209
	v_exp_f32_e32 v113, v113
	v_bfe_i32 v211, v208, 19, 1
	v_and_b32_e32 v112, v112, v210
	v_exp_f32_e32 v114, v114
	v_bfe_i32 v209, v208, 24, 1
	v_and_b32_e32 v113, v113, v211
	v_exp_f32_e32 v115, v115
	v_bfe_i32 v210, v208, 25, 1
	v_and_b32_e32 v114, v114, v209
	v_exp_f32_e32 v116, v116
	v_bfe_i32 v211, v208, 26, 1
	v_and_b32_e32 v115, v115, v210
	v_exp_f32_e32 v117, v117
	v_bfe_i32 v209, v208, 27, 1
	v_and_b32_e32 v116, v116, v211
	s_nop 0
	v_and_b32_e32 v117, v117, v209
	v_cvt_pk_bf16_f32 v208, v102, v103
	v_cvt_pk_bf16_f32 v209, v104, v105
	v_cvt_pk_bf16_f32 v210, v106, v107
	v_cvt_pk_bf16_f32 v211, v108, v109
	v_cvt_pk_bf16_f32 v212, v110, v111
	v_cvt_pk_bf16_f32 v213, v112, v113
	v_cvt_pk_bf16_f32 v214, v114, v115
	v_cvt_pk_bf16_f32 v215, v116, v117
	s_setprio 1
	s_waitcnt lgkmcnt(7)
	v_mfma_f32_32x32x16_bf16 v[86:101], v[216:219], v[126:129], v[70:85]
	ds_read2_b64 v[216:219], v204 offset0:0 offset1:2
	s_waitcnt lgkmcnt(7)
	v_mfma_f32_32x32x16_bf16 v[86:101], v[228:231], v[0:3], v[86:101]
	ds_read2_b64 v[228:231], v204 offset0:4 offset1:6
	s_waitcnt lgkmcnt(7)
	v_mfma_f32_32x32x16_bf16 v[86:101], v[232:235], v[118:121], v[86:101]
	v_add_u32_e32 v207, 4864, v204
	ds_read2_b64 v[232:235], v207 offset0:0 offset1:2
	s_waitcnt lgkmcnt(7)
	v_mfma_f32_32x32x16_bf16 v[86:101], v[236:239], v[122:125], v[86:101]
	ds_read2_b64 v[236:239], v207 offset0:4 offset1:6
	s_waitcnt lgkmcnt(7)
	v_mfma_f32_32x32x16_bf16 v[86:101], v[240:243], v[130:133], v[86:101]
	v_add_u32_e32 v207, 9728, v204
	ds_read2_b64 v[240:243], v207 offset0:0 offset1:2
	s_waitcnt lgkmcnt(7)
	v_mfma_f32_32x32x16_bf16 v[86:101], v[244:247], v[134:137], v[86:101]
	ds_read2_b64 v[244:247], v207 offset0:4 offset1:6
	s_waitcnt lgkmcnt(7)
	v_mfma_f32_32x32x16_bf16 v[86:101], v[248:251], v[138:141], v[86:101]
	v_add_u32_e32 v207, 14592, v204
	ds_read2_b64 v[248:251], v207 offset0:0 offset1:2
	s_waitcnt lgkmcnt(7)
; #define LAS __attribute__((address_space(3)))
; __device__ __forceinline__ unsigned pk2(float lo, float hi) { f32x2_t v = {lo, hi}; bf16x2_t b = __builtin_convertvector(v, bf16x2_t); return __builtin_bit_cast(unsigned, b); }
; __device__ __forceinline__ f32x16 mfma32(bf16x8 a, bf16x8 b, f32x16 c) { return __builtin_amdgcn_mfma_f32_32x32x16_bf16(a, b, c, 0, 0, 0); }
; __device__ __forceinline__ void dsa_unit32(const Args& a, LAS unsigned char* lds, const LAS unsigned long long* maskl, int b, int qb, int tid, int wave, int lane) {
;     ...
;         for (int kh = 0; kh < 2; ++kh) {
;             const unsigned mh = (unsigned)(mw >> (32 * kh + 4 * hi));
;             float p[16];
; #pragma unroll
;             for (int i = 0; i < 16; ++i) { const float e = __builtin_amdgcn_exp2f(S2[kh][i]);
;                 const int keep = __builtin_amdgcn_sbfe((int)mh, 8 * (i >> 2) + (i & 3), 1);
;                 p[i] = __builtin_bit_cast(float, __builtin_bit_cast(int, e) & keep); l += p[i]; }
;             u32x4 w0, w1;
;             w0.x = pk2(p[0], p[1]); w0.y = pk2(p[2], p[3]); w0.z = pk2(p[4], p[5]); w0.w = pk2(p[6], p[7]);
;             w1.x = pk2(p[8], p[9]); w1.y = pk2(p[10], p[11]); w1.z = pk2(p[12], p[13]); w1.w = pk2(p[14], p[15]);
;             const bf16x8 pa = __builtin_bit_cast(bf16x8, w0), pb = __builtin_bit_cast(bf16x8, w1);
;             __builtin_amdgcn_s_setprio(1);
; #pragma unroll
;             for (int ct = 0; ct < 4; ++ct) {
;                 const LAS bf16* vr = Vs + (32 * ct + l31) * VS + 4 * hi + 32 * kh;
;                 O[ct] = mfma32(cat8(*(const LAS u32x2*)(vr), *(const LAS u32x2*)(vr + 8)), pa, O[ct]);
;                 O[ct] = mfma32(cat8(*(const LAS u32x2*)(vr + 16), *(const LAS u32x2*)(vr + 24)), pb, O[ct]);
;             }
;             __builtin_amdgcn_s_setprio(0);
;         }
	v_mfma_f32_32x32x16_bf16 v[86:101], v[222:225], v[142:145], v[86:101]
	ds_read2_b64 v[222:225], v207 offset0:4 offset1:6
	s_setprio 0
	v_add_f32_e32 v194, v194, v102
	v_add_f32_e32 v194, v103, v194
	v_add_f32_e32 v194, v104, v194
	v_add_f32_e32 v194, v105, v194
	v_add_f32_e32 v194, v106, v194
	v_add_f32_e32 v194, v107, v194
	v_add_f32_e32 v194, v108, v194
	v_add_f32_e32 v194, v109, v194
	v_add_f32_e32 v194, v110, v194
	v_add_f32_e32 v194, v111, v194
	v_add_f32_e32 v194, v112, v194
	v_add_f32_e32 v194, v113, v194
	v_add_f32_e32 v194, v114, v194
	v_add_f32_e32 v194, v115, v194
	v_add_f32_e32 v194, v116, v194
	v_add_f32_e32 v194, v117, v194
	v_lshrrev_b64 v[110:111], v184, v[220:221]
	v_exp_f32_e32 v86, v86
	v_bfe_i32 v111, v110, 0, 1
	v_exp_f32_e32 v87, v87
	v_bfe_i32 v112, v110, 1, 1
	v_and_b32_e32 v86, v86, v111
	v_exp_f32_e32 v88, v88
	v_bfe_i32 v113, v110, 2, 1
	v_and_b32_e32 v87, v87, v112
	v_exp_f32_e32 v89, v89
	v_bfe_i32 v111, v110, 3, 1
	v_and_b32_e32 v88, v88, v113
	v_exp_f32_e32 v90, v90
	v_bfe_i32 v112, v110, 8, 1
	v_and_b32_e32 v89, v89, v111
	v_exp_f32_e32 v91, v91
	v_bfe_i32 v113, v110, 9, 1
	v_and_b32_e32 v90, v90, v112
	v_exp_f32_e32 v92, v92
	v_bfe_i32 v111, v110, 10, 1
	v_and_b32_e32 v91, v91, v113
	v_exp_f32_e32 v93, v93
	v_bfe_i32 v112, v110, 11, 1
	v_and_b32_e32 v92, v92, v111
	v_exp_f32_e32 v94, v94
	v_bfe_i32 v113, v110, 16, 1
	v_and_b32_e32 v93, v93, v112
	v_exp_f32_e32 v95, v95
	v_bfe_i32 v111, v110, 17, 1
	v_and_b32_e32 v94, v94, v113
	v_exp_f32_e32 v96, v96
	v_bfe_i32 v112, v110, 18, 1
	v_and_b32_e32 v95, v95, v111
	v_exp_f32_e32 v97, v97
	v_bfe_i32 v113, v110, 19, 1
	v_and_b32_e32 v96, v96, v112
	v_exp_f32_e32 v98, v98
	v_bfe_i32 v111, v110, 24, 1
	v_and_b32_e32 v97, v97, v113
	v_exp_f32_e32 v99, v99
	v_bfe_i32 v112, v110, 25, 1
	v_and_b32_e32 v98, v98, v111
	v_exp_f32_e32 v100, v100
	v_bfe_i32 v113, v110, 26, 1
	v_and_b32_e32 v99, v99, v112
	v_exp_f32_e32 v101, v101
	v_bfe_i32 v111, v110, 27, 1
	v_and_b32_e32 v100, v100, v113
	s_nop 0
	v_and_b32_e32 v101, v101, v111
	v_cvt_pk_bf16_f32 v102, v86, v87
	v_cvt_pk_bf16_f32 v103, v88, v89
	v_cvt_pk_bf16_f32 v104, v90, v91
	v_cvt_pk_bf16_f32 v105, v92, v93
	v_cvt_pk_bf16_f32 v106, v94, v95
	v_cvt_pk_bf16_f32 v107, v96, v97
	v_cvt_pk_bf16_f32 v108, v98, v99
	v_cvt_pk_bf16_f32 v109, v100, v101
	s_nop 1
	s_setprio 1
	s_waitcnt lgkmcnt(7)
	v_mfma_f32_32x32x16_bf16 v[54:69], v[216:219], v[208:211], v[54:69]
	ds_read2_b64 v[216:219], v204 offset0:8 offset1:10
	s_waitcnt lgkmcnt(7)
	v_mfma_f32_32x32x16_bf16 v[54:69], v[228:231], v[212:215], v[54:69]
	ds_read2_b64 v[228:231], v204 offset0:12 offset1:14
	s_waitcnt lgkmcnt(7)
	v_mfma_f32_32x32x16_bf16 v[38:53], v[232:235], v[208:211], v[38:53]
	v_add_u32_e32 v207, 4864, v204
	ds_read2_b64 v[232:235], v207 offset0:8 offset1:10
	s_waitcnt lgkmcnt(7)
	v_mfma_f32_32x32x16_bf16 v[38:53], v[236:239], v[212:215], v[38:53]
	ds_read2_b64 v[236:239], v207 offset0:12 offset1:14
	s_waitcnt lgkmcnt(7)
	v_mfma_f32_32x32x16_bf16 v[22:37], v[240:243], v[208:211], v[22:37]
	v_add_u32_e32 v207, 9728, v204
	ds_read2_b64 v[240:243], v207 offset0:8 offset1:10
	s_waitcnt lgkmcnt(7)
	v_mfma_f32_32x32x16_bf16 v[22:37], v[244:247], v[212:215], v[22:37]
	ds_read2_b64 v[244:247], v207 offset0:12 offset1:14
	s_waitcnt lgkmcnt(7)
	v_mfma_f32_32x32x16_bf16 v[6:21], v[248:251], v[208:211], v[6:21]
	v_add_u32_e32 v207, 14592, v204
	ds_read2_b64 v[248:251], v207 offset0:8 offset1:10
	s_waitcnt lgkmcnt(7)
	v_mfma_f32_32x32x16_bf16 v[6:21], v[222:225], v[212:215], v[6:21]
	ds_read2_b64 v[222:225], v207 offset0:12 offset1:14
	s_waitcnt lgkmcnt(7)
	v_mfma_f32_32x32x16_bf16 v[54:69], v[216:219], v[102:105], v[54:69]
	v_add_f32_e32 v194, v194, v86
	v_add_f32_e32 v194, v87, v194
	s_waitcnt lgkmcnt(6)
	v_mfma_f32_32x32x16_bf16 v[54:69], v[228:231], v[106:109], v[54:69]
	v_add_f32_e32 v194, v88, v194
	v_add_f32_e32 v194, v89, v194
	s_waitcnt lgkmcnt(5)
	v_mfma_f32_32x32x16_bf16 v[38:53], v[232:235], v[102:105], v[38:53]
	v_add_f32_e32 v194, v90, v194
	v_add_f32_e32 v194, v91, v194
	s_waitcnt lgkmcnt(4)
	v_mfma_f32_32x32x16_bf16 v[38:53], v[236:239], v[106:109], v[38:53]
	v_add_f32_e32 v194, v92, v194
	v_add_f32_e32 v194, v93, v194
	s_waitcnt lgkmcnt(3)
	v_mfma_f32_32x32x16_bf16 v[22:37], v[240:243], v[102:105], v[22:37]
	v_add_f32_e32 v194, v94, v194
	v_add_f32_e32 v194, v95, v194
	s_waitcnt lgkmcnt(2)
	v_mfma_f32_32x32x16_bf16 v[22:37], v[244:247], v[106:109], v[22:37]
	v_add_f32_e32 v194, v96, v194
	v_add_f32_e32 v194, v97, v194
	s_waitcnt lgkmcnt(1)
	v_mfma_f32_32x32x16_bf16 v[6:21], v[248:251], v[102:105], v[6:21]
	v_add_f32_e32 v194, v98, v194
	v_add_f32_e32 v194, v99, v194
	s_waitcnt lgkmcnt(0)
	v_mfma_f32_32x32x16_bf16 v[6:21], v[222:225], v[106:109], v[6:21]
	v_add_f32_e32 v194, v100, v194
	v_add_f32_e32 v194, v101, v194
	s_setprio 0
.Ldsa_J1:
	s_andn2_b64 vcc, exec, s[0:1]
	s_cbranch_vccnz .LBB0_1301
	s_waitcnt vmcnt(3)
	ds_write_b128 v196, v[146:149]
	s_waitcnt vmcnt(1)
	ds_write2_b64 v198, v[154:155], v[156:157] offset1:1
	ds_write_b128 v199, v[150:153]
	s_waitcnt vmcnt(0)
	ds_write2_b64 v201, v[158:159], v[160:161] offset1:1
	s_branch .LBB0_1301
